# GLA output phase: the 16-wide decay projection runs on f32 matrix cores (v_mfma_f32_16x16x4_f32, exact f32) with logsigmoid on the tiles and the running sum over t as a second LDS pass, replacing the
# speedup vs baseline: 1.0029x; 1.0029x over previous
.LBB0_465:
	s_cmp_lt_i32 s60, 8
	s_cselect_b64 s[0:1], -1, 0
	s_cmp_gt_i32 s61, 7
	s_cselect_b64 s[2:3], -1, 0
	s_and_b64 s[0:1], s[0:1], s[2:3]
	s_andn2_b64 vcc, exec, s[0:1]
	s_cbranch_vccnz .LBB0_512
	s_cmpk_gt_i32 s20, 0xff
	s_cbranch_scc1 .LBB0_476
	s_ashr_i32 s21, s20, 31
	s_lshl_b32 s4, s20, 6
	s_lshl_b64 s[0:1], s[20:21], 12
	s_add_u32 s0, s58, s0
	s_addc_u32 s1, s59, s1
	v_lshlrev_b32_e32 v78, 3, v0
	v_mov_b32_e32 v79, 0
	v_lshl_add_u64 v[2:3], s[0:1], 0, v[78:79]
	v_add_co_u32_e32 v2, vcc, 0x200000, v2
	v_and_b32_e32 v161, 0xff, v0
	s_nop 0
	v_addc_co_u32_e32 v3, vcc, 0, v3, vcc
	v_lshlrev_b32_e32 v150, 2, v161
	v_mov_b32_e32 v151, v79
	s_waitcnt vmcnt(0)
	v_readlane_b32 s98, v254, 20
	v_lshrrev_b32_e32 v246, 4, v1
	v_and_b32_e32 v247, 15, v1
	v_lshlrev_b32_e32 v246, 12, v246
	s_lshl_b32 s98, s98, 7
	v_lshl_add_u32 v247, v247, 2, s98
	v_add_u32_e32 v246, v246, v247
	global_load_dword v236, v246, s[40:41]
	global_load_dword v237, v246, s[40:41] offset:1024
	global_load_dword v238, v246, s[40:41] offset:2048
	global_load_dword v239, v246, s[40:41] offset:3072
	global_load_dword v240, v246, s[40:41] offset:64
	global_load_dword v241, v246, s[40:41] offset:1088
	global_load_dword v242, v246, s[40:41] offset:2112
	global_load_dword v243, v246, s[40:41] offset:3136
	global_load_dword v244, v247, s[42:43]
	global_load_dword v245, v247, s[42:43] offset:64
	global_load_dwordx2 v[164:165], v[2:3], off
	v_lshl_add_u64 v[2:3], s[40:41], 0, v[150:151]
	s_movk_i32 s0, 0x1000
	s_nop 0
	v_add_co_u32_e32 v4, vcc, s0, v2
	s_movk_i32 s0, 0x2000
	s_nop 0
	v_addc_co_u32_e32 v5, vcc, 0, v3, vcc
	v_add_co_u32_e32 v6, vcc, s0, v2
	v_lshlrev_b32_e32 v187, 2, v0
	s_nop 0
	v_addc_co_u32_e32 v7, vcc, 0, v3, vcc
	s_movk_i32 s0, 0x3000
	v_or_b32_e32 v8, 0xc00, v187
	v_add_co_u32_e32 v2, vcc, s0, v2
	s_add_u32 s0, s58, 0x8c00000
	v_or_b32_e32 v9, 0x1c00, v187
	v_or_b32_e32 v10, 0x2c00, v187
	v_addc_co_u32_e32 v3, vcc, 0, v3, vcc
	global_load_dword v142, v8, s[40:41]
	global_load_dword v147, v[4:5], off offset:1024
	global_load_dword v145, v[4:5], off offset:2048
	global_load_dword v143, v9, s[40:41]
	global_load_dword v134, v10, s[40:41]
	global_load_dword v139, v[2:3], off
	global_load_dword v141, v[2:3], off offset:1024
	global_load_dword v137, v[2:3], off offset:2048
	v_or_b32_e32 v2, 0x3c00, v187
	s_addc_u32 s1, s59, 0
	v_lshrrev_b32_e32 v160, 5, v0
	s_movk_i32 s12, 0xc00
	global_load_dword v135, v2, s[40:41]
	global_load_dword v148, v150, s[40:41]
	global_load_dword v146, v150, s[40:41] offset:1024
	global_load_dword v144, v150, s[40:41] offset:2048
	global_load_dword v149, v[6:7], off offset:-4096
	global_load_dword v138, v[6:7], off
	global_load_dword v140, v[6:7], off offset:1024
	global_load_dword v136, v[6:7], off offset:2048
	global_load_dword v162, v150, s[42:43]
	v_or_b32_e32 v2, s4, v160
	v_mov_b64_e32 v[18:19], s[0:1]
	v_lshlrev_b32_e32 v6, 4, v0
	v_mad_i64_i32 v[2:3], s[2:3], v2, s12, v[18:19]
	v_and_b32_e32 v4, 0x1f0, v6
	v_mov_b32_e32 v5, v79
	v_or_b32_e32 v7, 0x200, v0
	v_lshl_add_u64 v[2:3], v[2:3], 0, v[4:5]
	v_lshrrev_b32_e32 v159, 5, v7
	global_load_dwordx4 v[74:77], v[2:3], off
	global_load_dwordx4 v[70:73], v[2:3], off offset:512
	v_or_b32_e32 v2, s4, v159
	v_mad_i64_i32 v[2:3], s[2:3], v2, s12, v[18:19]
	v_or_b32_e32 v20, 0x400, v0
	v_lshl_add_u64 v[2:3], v[2:3], 0, v[4:5]
	v_lshrrev_b32_e32 v158, 5, v20
	global_load_dwordx4 v[66:69], v[2:3], off
	global_load_dwordx4 v[62:65], v[2:3], off offset:512
	v_or_b32_e32 v2, s4, v158
	v_mad_i64_i32 v[2:3], s[2:3], v2, s12, v[18:19]
	v_or_b32_e32 v22, 0x600, v0
	v_lshl_add_u64 v[2:3], v[2:3], 0, v[4:5]
	v_lshrrev_b32_e32 v151, 5, v22
	global_load_dwordx4 v[58:61], v[2:3], off
	global_load_dwordx4 v[54:57], v[2:3], off offset:512
	v_or_b32_e32 v2, s4, v151
	v_mad_i64_i32 v[2:3], s[2:3], v2, s12, v[18:19]
	v_lshrrev_b32_e32 v152, 6, v0
	v_lshl_add_u64 v[2:3], v[2:3], 0, v[4:5]
	v_or_b32_e32 v24, s4, v152
	global_load_dwordx4 v[50:53], v[2:3], off
	global_load_dwordx4 v[10:13], v[2:3], off offset:512
	v_mad_i64_i32 v[2:3], s[2:3], v24, s12, v[18:19]
	v_and_b32_e32 v80, 0x3f0, v6
	v_mov_b32_e32 v81, v79
	v_lshrrev_b32_e32 v153, 6, v7
	v_lshl_add_u64 v[14:15], v[2:3], 0, v[80:81]
	v_or_b32_e32 v2, s4, v153
	v_mad_i64_i32 v[2:3], s[2:3], v2, s12, v[18:19]
	v_lshrrev_b32_e32 v154, 6, v20
	v_lshl_add_u64 v[16:17], v[2:3], 0, v[80:81]
	global_load_dwordx4 v[6:9], v[14:15], off offset:1024
	global_load_dwordx4 v[2:5], v[16:17], off offset:1024
	v_or_b32_e32 v14, s4, v154
	v_mad_i64_i32 v[14:15], s[2:3], v14, s12, v[18:19]
	v_lshrrev_b32_e32 v155, 6, v22
	v_lshl_add_u64 v[20:21], v[14:15], 0, v[80:81]
	v_or_b32_e32 v14, s4, v155
	v_mad_i64_i32 v[14:15], s[2:3], v14, s12, v[18:19]
	v_lshl_add_u64 v[22:23], v[14:15], 0, v[80:81]
	global_load_dwordx4 v[30:33], v[20:21], off offset:1024
	global_load_dwordx4 v[14:17], v[22:23], off offset:1024
	v_or_b32_e32 v22, 0xa00, v0
	v_lshrrev_b32_e32 v156, 6, v22
	v_or_b32_e32 v20, 32, v24
	v_or_b32_e32 v22, s4, v156
	v_mad_i64_i32 v[20:21], s[2:3], v20, s12, v[18:19]
	v_mad_i64_i32 v[22:23], s[2:3], v22, s12, v[18:19]
	v_lshl_add_u64 v[20:21], v[20:21], 0, v[80:81]
	v_lshl_add_u64 v[22:23], v[22:23], 0, v[80:81]
	global_load_dwordx4 v[38:41], v[20:21], off offset:1024
	global_load_dwordx4 v[34:37], v[22:23], off offset:1024
	v_or_b32_e32 v22, 0xe00, v0
	v_lshrrev_b32_e32 v157, 6, v22
	v_or_b32_e32 v20, 48, v24
	v_or_b32_e32 v22, s4, v157
	v_mad_i64_i32 v[20:21], s[2:3], v20, s12, v[18:19]
	v_mad_i64_i32 v[18:19], s[2:3], v22, s12, v[18:19]
	v_readlane_b32 s2, v254, 21
	s_lshr_b32 s2, s2, 7
	s_lshl_b32 s3, s20, 2
	s_add_i32 s2, s3, s2
	s_ashr_i32 s3, s2, 31
	s_lshl_b64 s[2:3], s[2:3], 14
	v_lshrrev_b32_e32 v166, 5, v1
	s_add_u32 s2, s58, s2
	s_addc_u32 s3, s59, s3
	v_lshlrev_b32_e32 v182, 4, v166
	v_mov_b32_e32 v183, v79
	v_lshl_add_u64 v[82:83], s[2:3], 0, v[182:183]
	s_mov_b64 s[2:3], 0xe400000
	v_and_b32_e32 v185, 31, v0
	v_lshl_add_u64 v[26:27], v[82:83], 0, s[2:3]
	s_mov_b64 s[2:3], 0xe400020
	v_lshlrev_b32_e32 v28, 7, v185
	v_lshl_add_u64 v[94:95], v[82:83], 0, s[2:3]
	s_mov_b64 s[2:3], 0xe400040
	v_mov_b32_e32 v29, v79
	v_or_b32_e32 v114, 0x1000, v28
	v_mov_b32_e32 v115, v79
	v_or_b32_e32 v116, 0x2000, v28
	v_mov_b32_e32 v117, v79
	v_or_b32_e32 v168, 0x3000, v28
	v_mov_b32_e32 v169, v79
	v_lshl_add_u64 v[118:119], v[82:83], 0, s[2:3]
	s_mov_b64 s[2:3], 0xe400060
	v_lshl_add_u64 v[20:21], v[20:21], 0, v[80:81]
	v_lshl_add_u64 v[18:19], v[18:19], 0, v[80:81]
	v_lshl_add_u64 v[84:85], v[26:27], 0, v[28:29]
	v_lshl_add_u64 v[86:87], v[26:27], 0, v[114:115]
	v_lshl_add_u64 v[88:89], v[26:27], 0, v[116:117]
	v_lshl_add_u64 v[90:91], v[26:27], 0, v[168:169]
	v_lshl_add_u64 v[92:93], v[94:95], 0, v[114:115]
	v_lshl_add_u64 v[96:97], v[94:95], 0, v[116:117]
	v_lshl_add_u64 v[94:95], v[94:95], 0, v[168:169]
	v_lshl_add_u64 v[106:107], v[118:119], 0, v[114:115]
	v_lshl_add_u64 v[108:109], v[118:119], 0, v[116:117]
	v_lshl_add_u64 v[82:83], v[82:83], 0, s[2:3]
	global_load_dwordx4 v[46:49], v[20:21], off offset:1024
	global_load_dwordx4 v[42:45], v[18:19], off offset:1024
	s_nop 0
	global_load_dwordx4 v[18:21], v[86:87], off
	global_load_dwordx4 v[22:25], v[88:89], off
	global_load_dwordx4 v[26:29], v[84:85], off
	s_nop 0
	global_load_dwordx4 v[86:89], v[84:85], off offset:32
	global_load_dwordx4 v[102:105], v[90:91], off
	s_nop 0
	global_load_dwordx4 v[90:93], v[92:93], off
	s_nop 0
	global_load_dwordx4 v[98:101], v[96:97], off
	s_nop 0
	global_load_dwordx4 v[94:97], v[94:95], off
	s_nop 0
	global_load_dwordx4 v[110:113], v[106:107], off
	s_nop 0
	global_load_dwordx4 v[106:109], v[108:109], off
	v_lshl_add_u64 v[122:123], v[118:119], 0, v[168:169]
	global_load_dwordx4 v[130:133], v[84:85], off offset:64
	global_load_dwordx4 v[118:121], v[84:85], off offset:96
	v_lshl_add_u64 v[84:85], v[82:83], 0, v[114:115]
	global_load_dwordx4 v[126:129], v[122:123], off
	s_nop 0
	global_load_dwordx4 v[122:125], v[84:85], off
	v_lshl_add_u64 v[84:85], v[82:83], 0, v[116:117]
	v_lshl_add_u64 v[82:83], v[82:83], 0, v[168:169]
	global_load_dwordx4 v[114:117], v[84:85], off
	s_nop 0
	global_load_dwordx4 v[82:85], v[82:83], off
	s_add_i32 s2, 0, 0x23000
	v_lshrrev_b32_e32 v81, 3, v0
	v_add_u32_e32 v78, s2, v78
	v_and_b32_e32 v163, 32, v81
	s_waitcnt vmcnt(49)
	ds_write_b64 v78, v[164:165]
	v_lshl_add_u32 v78, v163, 6, s2
	s_waitcnt lgkmcnt(0)
	s_barrier
	v_lshrrev_b32_e32 v247, 4, v1
	v_and_b32_e32 v246, 15, v1
	v_lshlrev_b32_e32 v248, 6, v246
	v_lshl_add_u32 v248, v247, 4, v248
	v_add_u32_e32 v248, 0x23000, v248
	ds_read_b128 v[220:223], v248
	ds_read_b128 v[224:227], v248 offset:1024
	ds_read_b128 v[228:231], v248 offset:2048
	ds_read_b128 v[232:235], v248 offset:3072
	v_readlane_b32 s98, v254, 20
	v_lshlrev_b32_e32 v249, 12, v247
	v_lshl_add_u32 v249, v246, 2, v249
	s_lshl_b32 s99, s98, 7
	v_add_u32_e32 v249, s99, v249
	s_waitcnt lgkmcnt(0)
	v_mfma_f32_16x16x4_f32 v[188:191], v220, v236, 0
	v_mfma_f32_16x16x4_f32 v[192:195], v220, v240, 0
	v_mfma_f32_16x16x4_f32 v[196:199], v224, v236, 0
	v_mfma_f32_16x16x4_f32 v[200:203], v224, v240, 0
	v_mfma_f32_16x16x4_f32 v[204:207], v228, v236, 0
	v_mfma_f32_16x16x4_f32 v[208:211], v228, v240, 0
	v_mfma_f32_16x16x4_f32 v[212:215], v232, v236, 0
	v_mfma_f32_16x16x4_f32 v[216:219], v232, v240, 0
	v_mfma_f32_16x16x4_f32 v[188:191], v221, v237, v[188:191]
	v_mfma_f32_16x16x4_f32 v[192:195], v221, v241, v[192:195]
	v_mfma_f32_16x16x4_f32 v[196:199], v225, v237, v[196:199]
	v_mfma_f32_16x16x4_f32 v[200:203], v225, v241, v[200:203]
	v_mfma_f32_16x16x4_f32 v[204:207], v229, v237, v[204:207]
	v_mfma_f32_16x16x4_f32 v[208:211], v229, v241, v[208:211]
	v_mfma_f32_16x16x4_f32 v[212:215], v233, v237, v[212:215]
	v_mfma_f32_16x16x4_f32 v[216:219], v233, v241, v[216:219]
	v_mfma_f32_16x16x4_f32 v[188:191], v222, v238, v[188:191]
	v_mfma_f32_16x16x4_f32 v[192:195], v222, v242, v[192:195]
	v_mfma_f32_16x16x4_f32 v[196:199], v226, v238, v[196:199]
	v_mfma_f32_16x16x4_f32 v[200:203], v226, v242, v[200:203]
	v_mfma_f32_16x16x4_f32 v[204:207], v230, v238, v[204:207]
	v_mfma_f32_16x16x4_f32 v[208:211], v230, v242, v[208:211]
	v_mfma_f32_16x16x4_f32 v[212:215], v234, v238, v[212:215]
	v_mfma_f32_16x16x4_f32 v[216:219], v234, v242, v[216:219]
	v_mfma_f32_16x16x4_f32 v[188:191], v223, v239, v[188:191]
	v_mfma_f32_16x16x4_f32 v[192:195], v223, v243, v[192:195]
	v_mfma_f32_16x16x4_f32 v[196:199], v227, v239, v[196:199]
	v_mfma_f32_16x16x4_f32 v[200:203], v227, v243, v[200:203]
	v_mfma_f32_16x16x4_f32 v[204:207], v231, v239, v[204:207]
	v_mfma_f32_16x16x4_f32 v[208:211], v231, v243, v[208:211]
	v_mfma_f32_16x16x4_f32 v[212:215], v235, v239, v[212:215]
	v_mfma_f32_16x16x4_f32 v[216:219], v235, v243, v[216:219]
	s_nop 7
	s_nop 3
	v_add_f32_e32 v188, v188, v244
	v_add_f32_e32 v189, v189, v244
	v_add_f32_e32 v190, v190, v244
	v_add_f32_e32 v191, v191, v244
	v_max_f32_e32 v188, 0xc2a00000, v188
	v_max_f32_e32 v189, 0xc2a00000, v189
	v_max_f32_e32 v190, 0xc2a00000, v190
	v_max_f32_e32 v191, 0xc2a00000, v191
	v_mul_f32_e32 v188, 0xbfb8aa3b, v188
	v_mul_f32_e32 v189, 0xbfb8aa3b, v189
	v_mul_f32_e32 v190, 0xbfb8aa3b, v190
	v_mul_f32_e32 v191, 0xbfb8aa3b, v191
	v_exp_f32_e32 v188, v188
	v_exp_f32_e32 v189, v189
	v_exp_f32_e32 v190, v190
	v_exp_f32_e32 v191, v191
	v_add_f32_e32 v188, 1.0, v188
	v_add_f32_e32 v189, 1.0, v189
	v_add_f32_e32 v190, 1.0, v190
	v_add_f32_e32 v191, 1.0, v191
	v_log_f32_e32 v188, v188
	v_log_f32_e32 v189, v189
	v_log_f32_e32 v190, v190
	v_log_f32_e32 v191, v191
	v_mul_f32_e32 v188, 0x3f317218, v188
	v_mul_f32_e32 v189, 0x3f317218, v189
	v_mul_f32_e32 v190, 0x3f317218, v190
	v_mul_f32_e32 v191, 0x3f317218, v191
	ds_write_b32 v249, v188 offset:0
	ds_write_b32 v249, v189 offset:1024
	ds_write_b32 v249, v190 offset:2048
	ds_write_b32 v249, v191 offset:3072
	v_add_f32_e32 v192, v192, v245
	v_add_f32_e32 v193, v193, v245
	v_add_f32_e32 v194, v194, v245
	v_add_f32_e32 v195, v195, v245
	v_max_f32_e32 v192, 0xc2a00000, v192
	v_max_f32_e32 v193, 0xc2a00000, v193
	v_max_f32_e32 v194, 0xc2a00000, v194
	v_max_f32_e32 v195, 0xc2a00000, v195
	v_mul_f32_e32 v192, 0xbfb8aa3b, v192
	v_mul_f32_e32 v193, 0xbfb8aa3b, v193
	v_mul_f32_e32 v194, 0xbfb8aa3b, v194
	v_mul_f32_e32 v195, 0xbfb8aa3b, v195
	v_exp_f32_e32 v192, v192
	v_exp_f32_e32 v193, v193
	v_exp_f32_e32 v194, v194
	v_exp_f32_e32 v195, v195
	v_add_f32_e32 v192, 1.0, v192
	v_add_f32_e32 v193, 1.0, v193
	v_add_f32_e32 v194, 1.0, v194
	v_add_f32_e32 v195, 1.0, v195
	v_log_f32_e32 v192, v192
	v_log_f32_e32 v193, v193
	v_log_f32_e32 v194, v194
	v_log_f32_e32 v195, v195
	v_mul_f32_e32 v192, 0x3f317218, v192
	v_mul_f32_e32 v193, 0x3f317218, v193
	v_mul_f32_e32 v194, 0x3f317218, v194
	v_mul_f32_e32 v195, 0x3f317218, v195
	ds_write_b32 v249, v192 offset:64
	ds_write_b32 v249, v193 offset:1088
	ds_write_b32 v249, v194 offset:2112
	ds_write_b32 v249, v195 offset:3136
	v_add_f32_e32 v196, v196, v244
	v_add_f32_e32 v197, v197, v244
	v_add_f32_e32 v198, v198, v244
	v_add_f32_e32 v199, v199, v244
	v_max_f32_e32 v196, 0xc2a00000, v196
	v_max_f32_e32 v197, 0xc2a00000, v197
	v_max_f32_e32 v198, 0xc2a00000, v198
	v_max_f32_e32 v199, 0xc2a00000, v199
	v_mul_f32_e32 v196, 0xbfb8aa3b, v196
	v_mul_f32_e32 v197, 0xbfb8aa3b, v197
	v_mul_f32_e32 v198, 0xbfb8aa3b, v198
	v_mul_f32_e32 v199, 0xbfb8aa3b, v199
	v_exp_f32_e32 v196, v196
	v_exp_f32_e32 v197, v197
	v_exp_f32_e32 v198, v198
	v_exp_f32_e32 v199, v199
	v_add_f32_e32 v196, 1.0, v196
	v_add_f32_e32 v197, 1.0, v197
	v_add_f32_e32 v198, 1.0, v198
	v_add_f32_e32 v199, 1.0, v199
	v_log_f32_e32 v196, v196
	v_log_f32_e32 v197, v197
	v_log_f32_e32 v198, v198
	v_log_f32_e32 v199, v199
	v_mul_f32_e32 v196, 0x3f317218, v196
	v_mul_f32_e32 v197, 0x3f317218, v197
	v_mul_f32_e32 v198, 0x3f317218, v198
	v_mul_f32_e32 v199, 0x3f317218, v199
	ds_write_b32 v249, v196 offset:16384
	ds_write_b32 v249, v197 offset:17408
	ds_write_b32 v249, v198 offset:18432
	ds_write_b32 v249, v199 offset:19456
	v_add_f32_e32 v200, v200, v245
	v_add_f32_e32 v201, v201, v245
	v_add_f32_e32 v202, v202, v245
	v_add_f32_e32 v203, v203, v245
	v_max_f32_e32 v200, 0xc2a00000, v200
	v_max_f32_e32 v201, 0xc2a00000, v201
	v_max_f32_e32 v202, 0xc2a00000, v202
	v_max_f32_e32 v203, 0xc2a00000, v203
	v_mul_f32_e32 v200, 0xbfb8aa3b, v200
	v_mul_f32_e32 v201, 0xbfb8aa3b, v201
	v_mul_f32_e32 v202, 0xbfb8aa3b, v202
	v_mul_f32_e32 v203, 0xbfb8aa3b, v203
	v_exp_f32_e32 v200, v200
	v_exp_f32_e32 v201, v201
	v_exp_f32_e32 v202, v202
	v_exp_f32_e32 v203, v203
	v_add_f32_e32 v200, 1.0, v200
	v_add_f32_e32 v201, 1.0, v201
	v_add_f32_e32 v202, 1.0, v202
	v_add_f32_e32 v203, 1.0, v203
	v_log_f32_e32 v200, v200
	v_log_f32_e32 v201, v201
	v_log_f32_e32 v202, v202
	v_log_f32_e32 v203, v203
	v_mul_f32_e32 v200, 0x3f317218, v200
	v_mul_f32_e32 v201, 0x3f317218, v201
	v_mul_f32_e32 v202, 0x3f317218, v202
	v_mul_f32_e32 v203, 0x3f317218, v203
	ds_write_b32 v249, v200 offset:16448
	ds_write_b32 v249, v201 offset:17472
	ds_write_b32 v249, v202 offset:18496
	ds_write_b32 v249, v203 offset:19520
	v_add_f32_e32 v204, v204, v244
	v_add_f32_e32 v205, v205, v244
	v_add_f32_e32 v206, v206, v244
	v_add_f32_e32 v207, v207, v244
	v_max_f32_e32 v204, 0xc2a00000, v204
	v_max_f32_e32 v205, 0xc2a00000, v205
	v_max_f32_e32 v206, 0xc2a00000, v206
	v_max_f32_e32 v207, 0xc2a00000, v207
	v_mul_f32_e32 v204, 0xbfb8aa3b, v204
	v_mul_f32_e32 v205, 0xbfb8aa3b, v205
	v_mul_f32_e32 v206, 0xbfb8aa3b, v206
	v_mul_f32_e32 v207, 0xbfb8aa3b, v207
	v_exp_f32_e32 v204, v204
	v_exp_f32_e32 v205, v205
	v_exp_f32_e32 v206, v206
	v_exp_f32_e32 v207, v207
	v_add_f32_e32 v204, 1.0, v204
	v_add_f32_e32 v205, 1.0, v205
	v_add_f32_e32 v206, 1.0, v206
	v_add_f32_e32 v207, 1.0, v207
	v_log_f32_e32 v204, v204
	v_log_f32_e32 v205, v205
	v_log_f32_e32 v206, v206
	v_log_f32_e32 v207, v207
	v_mul_f32_e32 v204, 0x3f317218, v204
	v_mul_f32_e32 v205, 0x3f317218, v205
	v_mul_f32_e32 v206, 0x3f317218, v206
	v_mul_f32_e32 v207, 0x3f317218, v207
	ds_write_b32 v249, v204 offset:32768
	ds_write_b32 v249, v205 offset:33792
	ds_write_b32 v249, v206 offset:34816
	ds_write_b32 v249, v207 offset:35840
	v_add_f32_e32 v208, v208, v245
	v_add_f32_e32 v209, v209, v245
	v_add_f32_e32 v210, v210, v245
	v_add_f32_e32 v211, v211, v245
	v_max_f32_e32 v208, 0xc2a00000, v208
	v_max_f32_e32 v209, 0xc2a00000, v209
	v_max_f32_e32 v210, 0xc2a00000, v210
	v_max_f32_e32 v211, 0xc2a00000, v211
	v_mul_f32_e32 v208, 0xbfb8aa3b, v208
	v_mul_f32_e32 v209, 0xbfb8aa3b, v209
	v_mul_f32_e32 v210, 0xbfb8aa3b, v210
	v_mul_f32_e32 v211, 0xbfb8aa3b, v211
	v_exp_f32_e32 v208, v208
	v_exp_f32_e32 v209, v209
	v_exp_f32_e32 v210, v210
	v_exp_f32_e32 v211, v211
	v_add_f32_e32 v208, 1.0, v208
	v_add_f32_e32 v209, 1.0, v209
	v_add_f32_e32 v210, 1.0, v210
	v_add_f32_e32 v211, 1.0, v211
	v_log_f32_e32 v208, v208
	v_log_f32_e32 v209, v209
	v_log_f32_e32 v210, v210
	v_log_f32_e32 v211, v211
	v_mul_f32_e32 v208, 0x3f317218, v208
	v_mul_f32_e32 v209, 0x3f317218, v209
	v_mul_f32_e32 v210, 0x3f317218, v210
	v_mul_f32_e32 v211, 0x3f317218, v211
	ds_write_b32 v249, v208 offset:32832
	ds_write_b32 v249, v209 offset:33856
	ds_write_b32 v249, v210 offset:34880
	ds_write_b32 v249, v211 offset:35904
	v_add_f32_e32 v212, v212, v244
	v_add_f32_e32 v213, v213, v244
	v_add_f32_e32 v214, v214, v244
	v_add_f32_e32 v215, v215, v244
	v_max_f32_e32 v212, 0xc2a00000, v212
	v_max_f32_e32 v213, 0xc2a00000, v213
	v_max_f32_e32 v214, 0xc2a00000, v214
	v_max_f32_e32 v215, 0xc2a00000, v215
	v_mul_f32_e32 v212, 0xbfb8aa3b, v212
	v_mul_f32_e32 v213, 0xbfb8aa3b, v213
	v_mul_f32_e32 v214, 0xbfb8aa3b, v214
	v_mul_f32_e32 v215, 0xbfb8aa3b, v215
	v_exp_f32_e32 v212, v212
	v_exp_f32_e32 v213, v213
	v_exp_f32_e32 v214, v214
	v_exp_f32_e32 v215, v215
	v_add_f32_e32 v212, 1.0, v212
	v_add_f32_e32 v213, 1.0, v213
	v_add_f32_e32 v214, 1.0, v214
	v_add_f32_e32 v215, 1.0, v215
	v_log_f32_e32 v212, v212
	v_log_f32_e32 v213, v213
	v_log_f32_e32 v214, v214
	v_log_f32_e32 v215, v215
	v_mul_f32_e32 v212, 0x3f317218, v212
	v_mul_f32_e32 v213, 0x3f317218, v213
	v_mul_f32_e32 v214, 0x3f317218, v214
	v_mul_f32_e32 v215, 0x3f317218, v215
	ds_write_b32 v249, v212 offset:49152
	ds_write_b32 v249, v213 offset:50176
	ds_write_b32 v249, v214 offset:51200
	ds_write_b32 v249, v215 offset:52224
	v_add_f32_e32 v216, v216, v245
	v_add_f32_e32 v217, v217, v245
	v_add_f32_e32 v218, v218, v245
	v_add_f32_e32 v219, v219, v245
	v_max_f32_e32 v216, 0xc2a00000, v216
	v_max_f32_e32 v217, 0xc2a00000, v217
	v_max_f32_e32 v218, 0xc2a00000, v218
	v_max_f32_e32 v219, 0xc2a00000, v219
	v_mul_f32_e32 v216, 0xbfb8aa3b, v216
	v_mul_f32_e32 v217, 0xbfb8aa3b, v217
	v_mul_f32_e32 v218, 0xbfb8aa3b, v218
	v_mul_f32_e32 v219, 0xbfb8aa3b, v219
	v_exp_f32_e32 v216, v216
	v_exp_f32_e32 v217, v217
	v_exp_f32_e32 v218, v218
	v_exp_f32_e32 v219, v219
	v_add_f32_e32 v216, 1.0, v216
	v_add_f32_e32 v217, 1.0, v217
	v_add_f32_e32 v218, 1.0, v218
	v_add_f32_e32 v219, 1.0, v219
	v_log_f32_e32 v216, v216
	v_log_f32_e32 v217, v217
	v_log_f32_e32 v218, v218
	v_log_f32_e32 v219, v219
	v_mul_f32_e32 v216, 0x3f317218, v216
	v_mul_f32_e32 v217, 0x3f317218, v217
	v_mul_f32_e32 v218, 0x3f317218, v218
	v_mul_f32_e32 v219, 0x3f317218, v219
	ds_write_b32 v249, v216 offset:49216
	ds_write_b32 v249, v217 offset:50240
	ds_write_b32 v249, v218 offset:51264
	ds_write_b32 v249, v219 offset:52288
	s_waitcnt lgkmcnt(0)
	s_barrier
	v_and_b32_e32 v246, 0xff, v0
	s_lshr_b32 s99, s98, 2
	s_lshl_b32 s100, s99, 15
	v_lshl_add_u32 v248, v246, 2, s100
	v_mov_b32_e32 v247, 0
	ds_read_b32 v220, v248 offset:0
	ds_read_b32 v221, v248 offset:1024
	ds_read_b32 v222, v248 offset:2048
	ds_read_b32 v223, v248 offset:3072
	ds_read_b32 v224, v248 offset:4096
	ds_read_b32 v225, v248 offset:5120
	ds_read_b32 v226, v248 offset:6144
	ds_read_b32 v227, v248 offset:7168
	s_waitcnt lgkmcnt(7)
	v_fmac_f32_e32 v247, 0xbd800000, v220
	ds_write_b32 v248, v247 offset:0
	s_waitcnt lgkmcnt(7)
	v_fmac_f32_e32 v247, 0xbd800000, v221
	ds_write_b32 v248, v247 offset:1024
	s_waitcnt lgkmcnt(7)
	v_fmac_f32_e32 v247, 0xbd800000, v222
	ds_write_b32 v248, v247 offset:2048
	s_waitcnt lgkmcnt(7)
	v_fmac_f32_e32 v247, 0xbd800000, v223
	ds_write_b32 v248, v247 offset:3072
	s_waitcnt lgkmcnt(7)
	v_fmac_f32_e32 v247, 0xbd800000, v224
	ds_write_b32 v248, v247 offset:4096
	s_waitcnt lgkmcnt(7)
	v_fmac_f32_e32 v247, 0xbd800000, v225
	ds_write_b32 v248, v247 offset:5120
	s_waitcnt lgkmcnt(7)
	v_fmac_f32_e32 v247, 0xbd800000, v226
	ds_write_b32 v248, v247 offset:6144
	s_waitcnt lgkmcnt(7)
	v_fmac_f32_e32 v247, 0xbd800000, v227
	ds_write_b32 v248, v247 offset:7168
	s_waitcnt lgkmcnt(4)
	ds_read_b32 v220, v248 offset:8192
	ds_read_b32 v221, v248 offset:9216
	ds_read_b32 v222, v248 offset:10240
	ds_read_b32 v223, v248 offset:11264
	ds_read_b32 v224, v248 offset:12288
	ds_read_b32 v225, v248 offset:13312
	ds_read_b32 v226, v248 offset:14336
	ds_read_b32 v227, v248 offset:15360
	s_waitcnt lgkmcnt(7)
	v_fmac_f32_e32 v247, 0xbd800000, v220
	ds_write_b32 v248, v247 offset:8192
	s_waitcnt lgkmcnt(7)
	v_fmac_f32_e32 v247, 0xbd800000, v221
	ds_write_b32 v248, v247 offset:9216
	s_waitcnt lgkmcnt(7)
	v_fmac_f32_e32 v247, 0xbd800000, v222
	ds_write_b32 v248, v247 offset:10240
	s_waitcnt lgkmcnt(7)
	v_fmac_f32_e32 v247, 0xbd800000, v223
	ds_write_b32 v248, v247 offset:11264
	s_waitcnt lgkmcnt(7)
	v_fmac_f32_e32 v247, 0xbd800000, v224
	ds_write_b32 v248, v247 offset:12288
	s_waitcnt lgkmcnt(7)
	v_fmac_f32_e32 v247, 0xbd800000, v225
	ds_write_b32 v248, v247 offset:13312
	s_waitcnt lgkmcnt(7)
	v_fmac_f32_e32 v247, 0xbd800000, v226
	ds_write_b32 v248, v247 offset:14336
	s_waitcnt lgkmcnt(7)
	v_fmac_f32_e32 v247, 0xbd800000, v227
	ds_write_b32 v248, v247 offset:15360
	s_waitcnt lgkmcnt(4)
	ds_read_b32 v220, v248 offset:16384
	ds_read_b32 v221, v248 offset:17408
	ds_read_b32 v222, v248 offset:18432
	ds_read_b32 v223, v248 offset:19456
	ds_read_b32 v224, v248 offset:20480
	ds_read_b32 v225, v248 offset:21504
	ds_read_b32 v226, v248 offset:22528
	ds_read_b32 v227, v248 offset:23552
	s_waitcnt lgkmcnt(7)
	v_fmac_f32_e32 v247, 0xbd800000, v220
	ds_write_b32 v248, v247 offset:16384
	s_waitcnt lgkmcnt(7)
	v_fmac_f32_e32 v247, 0xbd800000, v221
	ds_write_b32 v248, v247 offset:17408
	s_waitcnt lgkmcnt(7)
	v_fmac_f32_e32 v247, 0xbd800000, v222
	ds_write_b32 v248, v247 offset:18432
	s_waitcnt lgkmcnt(7)
	v_fmac_f32_e32 v247, 0xbd800000, v223
	ds_write_b32 v248, v247 offset:19456
	s_waitcnt lgkmcnt(7)
	v_fmac_f32_e32 v247, 0xbd800000, v224
	ds_write_b32 v248, v247 offset:20480
	s_waitcnt lgkmcnt(7)
	v_fmac_f32_e32 v247, 0xbd800000, v225
	ds_write_b32 v248, v247 offset:21504
	s_waitcnt lgkmcnt(7)
	v_fmac_f32_e32 v247, 0xbd800000, v226
	ds_write_b32 v248, v247 offset:22528
	s_waitcnt lgkmcnt(7)
	v_fmac_f32_e32 v247, 0xbd800000, v227
	ds_write_b32 v248, v247 offset:23552
	s_waitcnt lgkmcnt(4)
	ds_read_b32 v220, v248 offset:24576
	ds_read_b32 v221, v248 offset:25600
	ds_read_b32 v222, v248 offset:26624
	ds_read_b32 v223, v248 offset:27648
	ds_read_b32 v224, v248 offset:28672
	ds_read_b32 v225, v248 offset:29696
	ds_read_b32 v226, v248 offset:30720
	ds_read_b32 v227, v248 offset:31744
	s_waitcnt lgkmcnt(7)
	v_fmac_f32_e32 v247, 0xbd800000, v220
	ds_write_b32 v248, v247 offset:24576
	s_waitcnt lgkmcnt(7)
	v_fmac_f32_e32 v247, 0xbd800000, v221
	ds_write_b32 v248, v247 offset:25600
	s_waitcnt lgkmcnt(7)
	v_fmac_f32_e32 v247, 0xbd800000, v222
	ds_write_b32 v248, v247 offset:26624
	s_waitcnt lgkmcnt(7)
	v_fmac_f32_e32 v247, 0xbd800000, v223
	ds_write_b32 v248, v247 offset:27648
	s_waitcnt lgkmcnt(7)
	v_fmac_f32_e32 v247, 0xbd800000, v224
	ds_write_b32 v248, v247 offset:28672
	s_waitcnt lgkmcnt(7)
	v_fmac_f32_e32 v247, 0xbd800000, v225
	ds_write_b32 v248, v247 offset:29696
	s_waitcnt lgkmcnt(7)
	v_fmac_f32_e32 v247, 0xbd800000, v226
	ds_write_b32 v248, v247 offset:30720
	s_waitcnt lgkmcnt(7)
	v_fmac_f32_e32 v247, 0xbd800000, v227
	ds_write_b32 v248, v247 offset:31744
	s_cmp_lg_u32 s99, 0
	s_cbranch_scc1 .Lcb_notot_p7
	v_lshl_add_u32 v246, v246, 2, 0
	v_add_u32_e32 v246, 0x24000, v246
	ds_write_b32 v246, v247
.Lcb_notot_p7:
	v_lshl_add_u32 v78, v185, 5, 0
	v_lshl_add_u32 v138, v160, 10, v78
	s_waitcnt vmcnt(32)
	s_waitcnt lgkmcnt(0)
	s_barrier
	ds_read_b128 v[134:137], v138
	ds_read_b128 v[138:141], v138 offset:16
	s_add_i32 s3, 0, 0x11000
	s_mov_b32 s2, 0x3e000000
	s_waitcnt vmcnt(31)
	v_lshlrev_b32_e32 v162, 16, v74
	s_waitcnt lgkmcnt(1)
	v_mul_f32_e32 v142, 0x3fb8aa3b, v134
	s_waitcnt lgkmcnt(0)
	v_mul_f32_e32 v143, 0x3fb8aa3b, v138
	v_exp_f32_e32 v144, v143
	v_mul_f32_e32 v143, 0x3fb8aa3b, v135
	v_exp_f32_e32 v142, v142
	v_exp_f32_e32 v143, v143
	v_mul_f32_e32 v147, 0x3fb8aa3b, v140
	v_mul_f32_e32 v146, 0x3fb8aa3b, v136
	v_exp_f32_e32 v148, v147
	v_mul_f32_e32 v147, 0x3fb8aa3b, v137
	v_exp_f32_e32 v146, v146
	v_exp_f32_e32 v147, v147
	v_mul_f32_e32 v145, 0x3fb8aa3b, v139
	v_exp_f32_e32 v145, v145
	v_pk_mul_f32 v[142:143], v[142:143], s[2:3] op_sel_hi:[1,0]
	v_and_b32_e32 v163, 0xffff0000, v74
	v_mul_f32_e32 v149, 0x3fb8aa3b, v141
	v_pk_mul_f32 v[142:143], v[142:143], v[162:163]
	v_exp_f32_e32 v149, v149
	v_cvt_pk_bf16_f32 v74, v142, v143
	v_pk_mul_f32 v[142:143], v[146:147], s[2:3] op_sel_hi:[1,0]
	v_lshlrev_b32_e32 v146, 16, v75
	v_and_b32_e32 v147, 0xffff0000, v75
	v_pk_mul_f32 v[142:143], v[142:143], v[146:147]
	v_mul_f32_e32 v134, 0xbfb8aa3b, v134
	v_mul_f32_e32 v135, 0xbfb8aa3b, v135
	v_cvt_pk_bf16_f32 v75, v142, v143
	v_pk_mul_f32 v[142:143], v[144:145], s[2:3] op_sel_hi:[1,0]
	v_lshlrev_b32_e32 v144, 16, v76
	v_and_b32_e32 v145, 0xffff0000, v76
	v_exp_f32_e32 v134, v134
	v_exp_f32_e32 v135, v135
	v_pk_mul_f32 v[142:143], v[142:143], v[144:145]
	v_mul_f32_e32 v136, 0xbfb8aa3b, v136
	v_mul_f32_e32 v137, 0xbfb8aa3b, v137
	v_cvt_pk_bf16_f32 v76, v142, v143
	v_pk_mul_f32 v[142:143], v[148:149], s[2:3] op_sel_hi:[1,0]
	v_lshlrev_b32_e32 v144, 16, v77
	v_and_b32_e32 v145, 0xffff0000, v77
	v_exp_f32_e32 v136, v136
	v_exp_f32_e32 v137, v137
	v_pk_mul_f32 v[142:143], v[142:143], v[144:145]
	v_mul_f32_e32 v138, 0xbfb8aa3b, v138
	v_mul_f32_e32 v139, 0xbfb8aa3b, v139
	v_cvt_pk_bf16_f32 v77, v142, v143
	s_waitcnt vmcnt(30)
	v_lshlrev_b32_e32 v142, 16, v70
	v_and_b32_e32 v143, 0xffff0000, v70
	v_exp_f32_e32 v138, v138
	v_exp_f32_e32 v139, v139
	v_pk_mul_f32 v[134:135], v[134:135], v[142:143]
	v_mul_f32_e32 v140, 0xbfb8aa3b, v140
	v_mul_f32_e32 v141, 0xbfb8aa3b, v141
	v_cvt_pk_bf16_f32 v70, v134, v135
	v_lshlrev_b32_e32 v134, 16, v71
	v_and_b32_e32 v135, 0xffff0000, v71
	v_exp_f32_e32 v140, v140
	v_exp_f32_e32 v141, v141
	v_pk_mul_f32 v[134:135], v[136:137], v[134:135]
	v_lshlrev_b32_e32 v81, 4, v185
	v_cvt_pk_bf16_f32 v71, v134, v135
	v_lshlrev_b32_e32 v134, 16, v72
	v_and_b32_e32 v135, 0xffff0000, v72
	v_pk_mul_f32 v[134:135], v[138:139], v[134:135]
	v_add_u32_e32 v150, s3, v81
	s_add_i32 s13, 0, 0x1a000
	v_cvt_pk_bf16_f32 v72, v134, v135
	v_lshlrev_b32_e32 v134, 16, v73
	v_and_b32_e32 v135, 0xffff0000, v73
	s_movk_i32 s8, 0x240
	v_add_u32_e32 v81, s13, v81
	v_pk_mul_f32 v[134:135], v[140:141], v[134:135]
	v_mad_u32_u24 v138, v160, s8, v150
	v_lshl_add_u32 v139, v159, 10, v78
	v_cvt_pk_bf16_f32 v73, v134, v135
	ds_read_b128 v[134:137], v139
	ds_write_b128 v138, v[74:77]
	v_mad_u32_u24 v74, v160, s8, v81
	ds_write_b128 v74, v[70:73]
	ds_read_b128 v[70:73], v139 offset:16
	s_waitcnt lgkmcnt(3)
	v_mul_f32_e32 v75, 0xbfb8aa3b, v134
	v_exp_f32_e32 v76, v75
	v_mul_f32_e32 v74, 0x3fb8aa3b, v134
	v_exp_f32_e32 v74, v74
	s_waitcnt lgkmcnt(0)
	v_mul_f32_e32 v75, 0x3fb8aa3b, v70
	v_exp_f32_e32 v134, v75
	v_mul_f32_e32 v75, 0x3fb8aa3b, v135
	v_exp_f32_e32 v75, v75
	v_mul_f32_e32 v139, 0x3fb8aa3b, v72
	v_mul_f32_e32 v138, 0x3fb8aa3b, v136
	v_exp_f32_e32 v140, v139
	v_mul_f32_e32 v139, 0x3fb8aa3b, v137
	v_exp_f32_e32 v138, v138
	v_exp_f32_e32 v139, v139
	v_mul_f32_e32 v77, 0xbfb8aa3b, v135
	v_mul_f32_e32 v135, 0x3fb8aa3b, v71
	v_exp_f32_e32 v135, v135
	v_pk_mul_f32 v[74:75], v[74:75], s[2:3] op_sel_hi:[1,0]
	s_waitcnt vmcnt(29)
	v_lshlrev_b32_e32 v142, 16, v66
	v_and_b32_e32 v143, 0xffff0000, v66
	v_mul_f32_e32 v141, 0x3fb8aa3b, v73
	v_pk_mul_f32 v[74:75], v[74:75], v[142:143]
	v_exp_f32_e32 v141, v141
	v_cvt_pk_bf16_f32 v66, v74, v75
	v_pk_mul_f32 v[74:75], v[138:139], s[2:3] op_sel_hi:[1,0]
	v_lshlrev_b32_e32 v138, 16, v67
	v_and_b32_e32 v139, 0xffff0000, v67
	v_pk_mul_f32 v[74:75], v[74:75], v[138:139]
	v_exp_f32_e32 v77, v77
	v_cvt_pk_bf16_f32 v67, v74, v75
	v_pk_mul_f32 v[74:75], v[134:135], s[2:3] op_sel_hi:[1,0]
	v_lshlrev_b32_e32 v134, 16, v68
	v_and_b32_e32 v135, 0xffff0000, v68
	v_pk_mul_f32 v[74:75], v[74:75], v[134:135]
	v_mul_f32_e32 v136, 0xbfb8aa3b, v136
	v_mul_f32_e32 v137, 0xbfb8aa3b, v137
	v_cvt_pk_bf16_f32 v68, v74, v75
	v_pk_mul_f32 v[74:75], v[140:141], s[2:3] op_sel_hi:[1,0]
	v_lshlrev_b32_e32 v134, 16, v69
	v_and_b32_e32 v135, 0xffff0000, v69
	v_exp_f32_e32 v136, v136
	v_exp_f32_e32 v137, v137
	v_pk_mul_f32 v[74:75], v[74:75], v[134:135]
	v_mul_f32_e32 v70, 0xbfb8aa3b, v70
	v_mul_f32_e32 v71, 0xbfb8aa3b, v71
	v_cvt_pk_bf16_f32 v69, v74, v75
	s_waitcnt vmcnt(28)
	v_lshlrev_b32_e32 v74, 16, v62
	v_and_b32_e32 v75, 0xffff0000, v62
	v_exp_f32_e32 v70, v70
	v_exp_f32_e32 v71, v71
	v_pk_mul_f32 v[74:75], v[76:77], v[74:75]
	v_mul_f32_e32 v72, 0xbfb8aa3b, v72
	v_mul_f32_e32 v73, 0xbfb8aa3b, v73
	v_cvt_pk_bf16_f32 v62, v74, v75
	v_lshlrev_b32_e32 v74, 16, v63
	v_and_b32_e32 v75, 0xffff0000, v63
	v_exp_f32_e32 v72, v72
	v_exp_f32_e32 v73, v73
	v_pk_mul_f32 v[74:75], v[136:137], v[74:75]
	v_add_u32_e32 v161, 0x24000, v78
	v_cvt_pk_bf16_f32 v63, v74, v75
	v_lshlrev_b32_e32 v74, 16, v64
	v_and_b32_e32 v75, 0xffff0000, v64
	v_pk_mul_f32 v[70:71], v[70:71], v[74:75]
	s_waitcnt vmcnt(27)
	v_lshlrev_b32_e32 v142, 16, v58
	v_cvt_pk_bf16_f32 v64, v70, v71
	v_lshlrev_b32_e32 v70, 16, v65
	v_and_b32_e32 v71, 0xffff0000, v65
	v_pk_mul_f32 v[70:71], v[72:73], v[70:71]
	v_and_b32_e32 v143, 0xffff0000, v58
	v_cvt_pk_bf16_f32 v65, v70, v71
	v_mad_u32_u24 v70, v159, s8, v150
	ds_write_b128 v70, v[66:69]
	v_mad_u32_u24 v66, v159, s8, v81
	ds_write_b128 v66, v[62:65]
	v_lshl_add_u32 v70, v158, 10, v78
	ds_read_b128 v[62:65], v161 offset:16
	ds_read_b128 v[66:69], v70 offset:16
	ds_read_b128 v[70:73], v70
	ds_read_b128 v[74:77], v161
	v_readlane_b32 s11, v254, 21
	s_lshr_b32 s5, s11, 1
	s_waitcnt lgkmcnt(2)
	v_pk_add_f32 v[66:67], v[66:67], v[62:63]
	v_pk_add_f32 v[68:69], v[68:69], v[64:65]
	s_waitcnt lgkmcnt(0)
	v_pk_add_f32 v[70:71], v[70:71], v[74:75]
	v_mul_f32_e32 v135, 0x3fb8aa3b, v66
	v_mul_f32_e32 v134, 0x3fb8aa3b, v70
	v_exp_f32_e32 v136, v135
	v_mul_f32_e32 v135, 0x3fb8aa3b, v71
	v_pk_add_f32 v[72:73], v[72:73], v[76:77]
	v_exp_f32_e32 v134, v134
	v_exp_f32_e32 v135, v135
	v_mul_f32_e32 v139, 0x3fb8aa3b, v68
	v_mul_f32_e32 v138, 0x3fb8aa3b, v72
	v_exp_f32_e32 v140, v139
	v_mul_f32_e32 v139, 0x3fb8aa3b, v73
	v_exp_f32_e32 v138, v138
	v_exp_f32_e32 v139, v139
	v_mul_f32_e32 v137, 0x3fb8aa3b, v67
	v_exp_f32_e32 v137, v137
	v_pk_mul_f32 v[134:135], v[134:135], s[2:3] op_sel_hi:[1,0]
	v_mul_f32_e32 v141, 0x3fb8aa3b, v69
	v_pk_mul_f32 v[134:135], v[134:135], v[142:143]
	v_exp_f32_e32 v141, v141
	v_cvt_pk_bf16_f32 v58, v134, v135
	v_pk_mul_f32 v[134:135], v[138:139], s[2:3] op_sel_hi:[1,0]
	v_lshlrev_b32_e32 v138, 16, v59
	v_and_b32_e32 v139, 0xffff0000, v59
	v_pk_mul_f32 v[134:135], v[134:135], v[138:139]
	v_mul_f32_e32 v70, 0xbfb8aa3b, v70
	v_mul_f32_e32 v71, 0xbfb8aa3b, v71
	v_cvt_pk_bf16_f32 v59, v134, v135
	v_pk_mul_f32 v[134:135], v[136:137], s[2:3] op_sel_hi:[1,0]
	v_lshlrev_b32_e32 v136, 16, v60
	v_and_b32_e32 v137, 0xffff0000, v60
	v_exp_f32_e32 v70, v70
	v_exp_f32_e32 v71, v71
	v_pk_mul_f32 v[134:135], v[134:135], v[136:137]
	v_mul_f32_e32 v72, 0xbfb8aa3b, v72
	v_mul_f32_e32 v73, 0xbfb8aa3b, v73
	v_cvt_pk_bf16_f32 v60, v134, v135
	v_pk_mul_f32 v[134:135], v[140:141], s[2:3] op_sel_hi:[1,0]
	v_lshlrev_b32_e32 v136, 16, v61
	v_and_b32_e32 v137, 0xffff0000, v61
	v_exp_f32_e32 v72, v72
	v_exp_f32_e32 v73, v73
	v_pk_mul_f32 v[134:135], v[134:135], v[136:137]
	v_mul_f32_e32 v66, 0xbfb8aa3b, v66
	v_mul_f32_e32 v67, 0xbfb8aa3b, v67
	v_cvt_pk_bf16_f32 v61, v134, v135
	s_waitcnt vmcnt(26)
	v_lshlrev_b32_e32 v134, 16, v54
	v_and_b32_e32 v135, 0xffff0000, v54
	v_exp_f32_e32 v66, v66
	v_exp_f32_e32 v67, v67
	v_pk_mul_f32 v[70:71], v[70:71], v[134:135]
	v_mul_f32_e32 v68, 0xbfb8aa3b, v68
	v_mul_f32_e32 v69, 0xbfb8aa3b, v69
	v_cvt_pk_bf16_f32 v54, v70, v71
	v_lshlrev_b32_e32 v70, 16, v55
	v_and_b32_e32 v71, 0xffff0000, v55
	v_exp_f32_e32 v68, v68
	v_exp_f32_e32 v69, v69
	v_pk_mul_f32 v[70:71], v[72:73], v[70:71]
	s_and_b32 s9, s5, 32
	v_cvt_pk_bf16_f32 v55, v70, v71
	v_lshlrev_b32_e32 v70, 16, v56
	v_and_b32_e32 v71, 0xffff0000, v56
	v_pk_mul_f32 v[66:67], v[66:67], v[70:71]
	s_waitcnt vmcnt(25)
	v_lshlrev_b32_e32 v70, 16, v50
	v_cvt_pk_bf16_f32 v56, v66, v67
	v_lshlrev_b32_e32 v66, 16, v57
	v_and_b32_e32 v67, 0xffff0000, v57
	v_pk_mul_f32 v[66:67], v[68:69], v[66:67]
	v_and_b32_e32 v71, 0xffff0000, v50
	v_cvt_pk_bf16_f32 v57, v66, v67
	v_mad_u32_u24 v66, v158, s8, v150
	ds_write_b128 v66, v[58:61]
	v_mad_u32_u24 v58, v158, s8, v81
	ds_write_b128 v58, v[54:57]
	v_lshl_add_u32 v58, v151, 10, v78
	ds_read_b128 v[54:57], v58
	ds_read_b128 v[58:61], v58 offset:16
	v_lshrrev_b32_e32 v183, 4, v1
	s_or_b32 s4, s4, s9
	s_and_b32 s6, s11, 0xffffff80
	s_waitcnt lgkmcnt(1)
	v_pk_add_f32 v[54:55], v[74:75], v[54:55]
	s_waitcnt lgkmcnt(0)
	v_pk_add_f32 v[58:59], v[62:63], v[58:59]
	v_pk_add_f32 v[60:61], v[64:65], v[60:61]
	v_mul_f32_e32 v63, 0x3fb8aa3b, v58
	v_mul_f32_e32 v62, 0x3fb8aa3b, v54
	v_exp_f32_e32 v64, v63
	v_mul_f32_e32 v63, 0x3fb8aa3b, v55
	v_pk_add_f32 v[56:57], v[76:77], v[56:57]
	v_exp_f32_e32 v62, v62
	v_exp_f32_e32 v63, v63
	v_mul_f32_e32 v67, 0x3fb8aa3b, v60
	v_mul_f32_e32 v66, 0x3fb8aa3b, v56
	v_exp_f32_e32 v68, v67
	v_mul_f32_e32 v67, 0x3fb8aa3b, v57
	v_exp_f32_e32 v66, v66
	v_exp_f32_e32 v67, v67
	v_mul_f32_e32 v65, 0x3fb8aa3b, v59
	v_exp_f32_e32 v65, v65
	v_pk_mul_f32 v[62:63], v[62:63], s[2:3] op_sel_hi:[1,0]
	v_mul_f32_e32 v69, 0x3fb8aa3b, v61
	v_pk_mul_f32 v[62:63], v[62:63], v[70:71]
	v_exp_f32_e32 v69, v69
	v_cvt_pk_bf16_f32 v50, v62, v63
	v_pk_mul_f32 v[62:63], v[66:67], s[2:3] op_sel_hi:[1,0]
	v_lshlrev_b32_e32 v66, 16, v51
	v_and_b32_e32 v67, 0xffff0000, v51
	v_pk_mul_f32 v[62:63], v[62:63], v[66:67]
	v_mul_f32_e32 v54, 0xbfb8aa3b, v54
	v_mul_f32_e32 v55, 0xbfb8aa3b, v55
	v_cvt_pk_bf16_f32 v51, v62, v63
	v_pk_mul_f32 v[62:63], v[64:65], s[2:3] op_sel_hi:[1,0]
	v_lshlrev_b32_e32 v64, 16, v52
	v_and_b32_e32 v65, 0xffff0000, v52
	v_exp_f32_e32 v54, v54
	v_exp_f32_e32 v55, v55
	v_pk_mul_f32 v[62:63], v[62:63], v[64:65]
	v_mul_f32_e32 v56, 0xbfb8aa3b, v56
	v_mul_f32_e32 v57, 0xbfb8aa3b, v57
	v_cvt_pk_bf16_f32 v52, v62, v63
	v_pk_mul_f32 v[62:63], v[68:69], s[2:3] op_sel_hi:[1,0]
	v_lshlrev_b32_e32 v64, 16, v53
	v_and_b32_e32 v65, 0xffff0000, v53
	v_exp_f32_e32 v56, v56
	v_exp_f32_e32 v57, v57
	v_pk_mul_f32 v[62:63], v[62:63], v[64:65]
	v_mul_f32_e32 v58, 0xbfb8aa3b, v58
	v_mul_f32_e32 v59, 0xbfb8aa3b, v59
	v_cvt_pk_bf16_f32 v53, v62, v63
	s_waitcnt vmcnt(24)
	v_lshlrev_b32_e32 v62, 16, v10
	v_and_b32_e32 v63, 0xffff0000, v10
	v_exp_f32_e32 v58, v58
	v_exp_f32_e32 v59, v59
	v_pk_mul_f32 v[54:55], v[54:55], v[62:63]
	v_mul_f32_e32 v60, 0xbfb8aa3b, v60
	v_mul_f32_e32 v61, 0xbfb8aa3b, v61
	v_cvt_pk_bf16_f32 v10, v54, v55
	v_lshlrev_b32_e32 v54, 16, v11
	v_and_b32_e32 v55, 0xffff0000, v11
	v_exp_f32_e32 v60, v60
	v_exp_f32_e32 v61, v61
	v_pk_mul_f32 v[54:55], v[56:57], v[54:55]
	s_movk_i32 s2, 0x440
	v_cvt_pk_bf16_f32 v11, v54, v55
	v_lshlrev_b32_e32 v54, 16, v12
	v_and_b32_e32 v55, 0xffff0000, v12
	v_pk_mul_f32 v[54:55], v[58:59], v[54:55]
	v_or_b32_e32 v198, s4, v183
	v_cvt_pk_bf16_f32 v12, v54, v55
	v_lshlrev_b32_e32 v54, 16, v13
	v_and_b32_e32 v55, 0xffff0000, v13
	v_pk_mul_f32 v[54:55], v[60:61], v[54:55]
	s_ashr_i32 s7, s6, 31
	v_cvt_pk_bf16_f32 v13, v54, v55
	v_mad_u32_u24 v54, v151, s8, v150
	ds_write_b128 v54, v[50:53]
	v_mad_u32_u24 v50, v151, s8, v81
	ds_write_b128 v50, v[10:13]
	v_add_u32_e32 v10, 0, v80
	v_mad_u32_u24 v11, v152, s2, v10
	s_waitcnt lgkmcnt(0)
	s_barrier
	s_waitcnt vmcnt(23)
	ds_write_b128 v11, v[6:9]
	v_mad_u32_u24 v6, v153, s2, v10
	s_waitcnt vmcnt(22)
	ds_write_b128 v6, v[2:5]
	v_mad_u32_u24 v2, v154, s2, v10
	s_waitcnt vmcnt(21)
	ds_write_b128 v2, v[30:33]
	v_mad_u32_u24 v2, v155, s2, v10
	s_waitcnt vmcnt(20)
	ds_write_b128 v2, v[14:17]
	s_waitcnt vmcnt(19)
	ds_write_b128 v11, v[38:41] offset:34816
	v_mad_u32_u24 v2, v156, s2, v10
	s_waitcnt vmcnt(18)
	ds_write_b128 v2, v[34:37]
	s_waitcnt vmcnt(17)
	ds_write_b128 v11, v[46:49] offset:52224
	v_mad_u32_u24 v2, v157, s2, v10
	s_waitcnt vmcnt(16)
	ds_write_b128 v2, v[42:45]
	v_mov_b64_e32 v[2:3], s[0:1]
	v_and_b32_e32 v191, 15, v0
	v_mad_i64_i32 v[4:5], s[0:1], v198, s12, v[2:3]
	s_lshl_b64 s[4:5], s[6:7], 1
	v_or_b32_e32 v196, 4, v198
	v_lshl_add_u64 v[4:5], v[4:5], 0, s[4:5]
	v_lshlrev_b32_e32 v78, 4, v191
	v_mad_i64_i32 v[6:7], s[0:1], v196, s12, v[2:3]
	v_lshl_add_u64 v[4:5], v[4:5], 0, v[78:79]
	v_lshl_add_u64 v[6:7], v[6:7], 0, s[4:5]
	v_or_b32_e32 v194, 8, v198
	s_waitcnt lgkmcnt(0)
	s_barrier
	v_lshl_add_u64 v[6:7], v[6:7], 0, v[78:79]
	global_load_dwordx4 v[162:165], v[4:5], off offset:2048
	global_load_dwordx4 v[158:161], v[6:7], off offset:2048
	v_mad_i64_i32 v[4:5], s[0:1], v194, s12, v[2:3]
	v_or_b32_e32 v192, 12, v198
	v_lshl_add_u64 v[4:5], v[4:5], 0, s[4:5]
	v_mad_i64_i32 v[6:7], s[0:1], v192, s12, v[2:3]
	v_lshl_add_u64 v[4:5], v[4:5], 0, v[78:79]
	v_lshl_add_u64 v[6:7], v[6:7], 0, s[4:5]
	v_or_b32_e32 v190, 16, v198
	v_lshl_add_u64 v[6:7], v[6:7], 0, v[78:79]
	global_load_dwordx4 v[154:157], v[4:5], off offset:2048
	global_load_dwordx4 v[150:153], v[6:7], off offset:2048
	v_mad_i64_i32 v[4:5], s[0:1], v190, s12, v[2:3]
	v_or_b32_e32 v188, 20, v198
	v_lshl_add_u64 v[4:5], v[4:5], 0, s[4:5]
	v_mad_i64_i32 v[6:7], s[0:1], v188, s12, v[2:3]
	v_lshl_add_u64 v[4:5], v[4:5], 0, v[78:79]
	v_lshl_add_u64 v[6:7], v[6:7], 0, s[4:5]
	v_or_b32_e32 v186, 24, v198
	v_lshl_add_u64 v[6:7], v[6:7], 0, v[78:79]
	global_load_dwordx4 v[146:149], v[4:5], off offset:2048
	global_load_dwordx4 v[142:145], v[6:7], off offset:2048
	v_mad_i64_i32 v[4:5], s[0:1], v186, s12, v[2:3]
	v_or_b32_e32 v184, 28, v198
	v_lshl_add_u64 v[4:5], v[4:5], 0, s[4:5]
	v_mad_i64_i32 v[2:3], s[0:1], v184, s12, v[2:3]
	v_lshl_add_u64 v[4:5], v[4:5], 0, v[78:79]
	v_lshl_add_u64 v[2:3], v[2:3], 0, s[4:5]
	v_lshl_add_u64 v[2:3], v[2:3], 0, v[78:79]
	global_load_dwordx4 v[138:141], v[4:5], off offset:2048
	global_load_dwordx4 v[134:137], v[2:3], off offset:2048
	s_add_i32 s13, s13, s6
	v_add_u32_e32 v2, s13, v182
	v_mad_u32_u24 v12, v185, s8, v2
	ds_read_b128 v[4:7], v12
	v_or_b32_e32 v3, s9, v185
	v_mul_u32_u24_e32 v3, 0x240, v3
	s_add_i32 s0, s6, s3
	v_add3_u32 v3, s0, v3, v182
	ds_read_b128 v[174:177], v3
	ds_read_b128 v[170:173], v3 offset:32
	ds_read_b128 v[8:11], v12 offset:32
	v_lshlrev_b32_e32 v193, 2, v166
	s_bitcmp1_b32 s11, 6
	s_cselect_b64 s[12:13], -1, 0
	s_waitcnt lgkmcnt(2)
	v_mfma_f32_32x32x16_bf16 v[66:81], v[4:7], v[174:177], 0
	ds_read_b128 v[4:7], v12 offset:64
	ds_read_b128 v[178:181], v3 offset:64
	v_cmp_le_u32_e64 s[0:1], v193, v185
	v_cmp_lt_u32_e64 s[2:3], v193, v185
	v_or_b32_e32 v40, 2, v193
	v_or_b32_e32 v41, 3, v193
	v_or_b32_e32 v37, 8, v193
	s_waitcnt lgkmcnt(2)
	v_mfma_f32_32x32x16_bf16 v[66:81], v[8:11], v[170:173], v[66:81]
	ds_read_b128 v[166:169], v3 offset:96
	ds_read_b128 v[8:11], v12 offset:96
	v_or_b32_e32 v43, 9, v193
	v_or_b32_e32 v42, 10, v193
	v_or_b32_e32 v38, 11, v193
	v_or_b32_e32 v35, 16, v193
	v_or_b32_e32 v33, 17, v193
	s_and_b64 vcc, exec, s[12:13]
	s_waitcnt lgkmcnt(2)
	v_mfma_f32_32x32x16_bf16 v[66:81], v[4:7], v[178:181], v[66:81]
	v_or_b32_e32 v39, 18, v193
	v_or_b32_e32 v36, 19, v193
	v_or_b32_e32 v34, 24, v193
	v_or_b32_e32 v32, 25, v193
	v_or_b32_e32 v31, 26, v193
	v_or_b32_e32 v30, 27, v193
	s_waitcnt lgkmcnt(0)
	v_mfma_f32_32x32x16_bf16 v[66:81], v[8:11], v[166:169], v[66:81]
	s_cbranch_vccnz .LBB0_471
	v_cmp_le_u32_e32 vcc, v40, v185
	s_nop 9
	v_cndmask_b32_e64 v67, 0, v67, s[2:3]
	v_cndmask_b32_e64 v66, 0, v66, s[0:1]
	v_cndmask_b32_e32 v68, 0, v68, vcc
	v_cmp_le_u32_e32 vcc, v41, v185
	s_nop 1
	v_cndmask_b32_e32 v69, 0, v69, vcc
	v_cmp_le_u32_e32 vcc, v37, v185
	s_nop 1
	v_cndmask_b32_e32 v70, 0, v70, vcc
	v_cmp_le_u32_e32 vcc, v43, v185
	s_nop 1
	v_cndmask_b32_e32 v71, 0, v71, vcc
	v_cmp_le_u32_e32 vcc, v42, v185
	s_nop 1
	v_cndmask_b32_e32 v72, 0, v72, vcc
	v_cmp_le_u32_e32 vcc, v38, v185
	s_nop 1
	v_cndmask_b32_e32 v73, 0, v73, vcc
	v_cmp_le_u32_e32 vcc, v35, v185
	s_nop 1
	v_cndmask_b32_e32 v74, 0, v74, vcc
	v_cmp_le_u32_e32 vcc, v33, v185
	s_nop 1
	v_cndmask_b32_e32 v75, 0, v75, vcc
	v_cmp_le_u32_e32 vcc, v39, v185
	s_nop 1
	v_cndmask_b32_e32 v76, 0, v76, vcc
	v_cmp_le_u32_e32 vcc, v36, v185
	s_nop 1
	v_cndmask_b32_e32 v77, 0, v77, vcc
	v_cmp_le_u32_e32 vcc, v34, v185
	s_nop 1
	v_cndmask_b32_e32 v78, 0, v78, vcc
	v_cmp_le_u32_e32 vcc, v32, v185
	s_nop 1
	v_cndmask_b32_e32 v79, 0, v79, vcc
	v_cmp_le_u32_e32 vcc, v31, v185
	s_nop 1
	v_cndmask_b32_e32 v80, 0, v80, vcc
	v_cmp_le_u32_e32 vcc, v30, v185
	s_nop 1
	v_cndmask_b32_e32 v81, 0, v81, vcc
